# plus LayerNorm wave sums via DPP and permlane swaps instead of LDS bpermute round trips (4 LN phases)
# speedup vs baseline: 1.0119x; 1.0097x over previous
; DI float bflo(u32 u) { return __uint_as_float(u << 16); }
; DI float bfhi(u32 u) { return __uint_as_float(u & 0xffff0000u); }
; template <typename XT>
; DI void ln1_phase(const Params& p, const XT* __restrict__ xin, const float* __restrict__ mm, const float* __restrict__ gain, const float* __restrict__ bias,
;                   float* __restrict__ of, bf16* __restrict__ ob) {
;     ...
;   for (int t = blockIdx.x * 4 + w; t < T_TOK; t += gridDim.x * 4) {
;     float v[16];
; #pragma unroll
;     for (int i = 0; i < 4; ++i) {
;       float4 a;
;       if constexpr (sizeof(XT) == 4) {
;         a = *(const float4*)((const float*)xin + (size_t)t * 1024 + 4 * lane + 256 * i);
;       } else {
;         const uint2 ab = *(const uint2*)((const bf16*)xin + (size_t)t * 1024 + 4 * lane + 256 * i);
;         a = make_float4(bflo(ab.x), bfhi(ab.x), bflo(ab.y), bfhi(ab.y));
;       }
;       float4 c = *(const float4*)(mm + (size_t)t * 1024 + 4 * lane + 256 * i);
;       v[4 * i] = DN_ALPHA * a.x + c.x; v[4 * i + 1] = DN_ALPHA * a.y + c.y; v[4 * i + 2] = DN_ALPHA * a.z + c.z; v[4 * i + 3] = DN_ALPHA * a.w + c.w;
;     }
;     float s = 0.f;
; #pragma unroll
;     for (int i = 0; i < 16; ++i) s += v[i];
;     float mu = wave_sum(s) * (1.f / 1024.f);
;     float q = 0.f;
; #pragma unroll
;     for (int i = 0; i < 16; ++i) { float d = v[i] - mu; q += d * d; }
;     float rstd = rsqrtf(wave_sum(q) * (1.f / 1024.f) + 1e-5f);
; #pragma unroll
;     for (int i = 0; i < 4; ++i) {
;       float4 gg = *(const float4*)(gain + 4 * lane + 256 * i);
;       float4 bb = *(const float4*)(bias + 4 * lane + 256 * i);
;       float4 o;
;       o.x = (v[4 * i] - mu) * rstd * gg.x + bb.x; o.y = (v[4 * i + 1] - mu) * rstd * gg.y + bb.y;
;       o.z = (v[4 * i + 2] - mu) * rstd * gg.z + bb.z; o.w = (v[4 * i + 3] - mu) * rstd * gg.w + bb.w;
;       if (of) *(float4*)(of + (size_t)t * 1024 + 4 * lane + 256 * i) = o;
.LBB0_539:
	v_ashrrev_i32_e32 v33, 31, v32
	v_lshlrev_b64 v[48:49], 12, v[32:33]
	v_lshl_add_u64 v[80:81], v[34:35], 0, v[48:49]
	v_lshl_add_u64 v[82:83], v[36:37], 0, v[48:49]
	global_load_dwordx4 v[48:51], v[80:81], off offset:3072
	global_load_dwordx4 v[52:55], v[82:83], off offset:3072
	global_load_dwordx4 v[56:59], v[82:83], off
	global_load_dwordx4 v[60:63], v[80:81], off
	global_load_dwordx4 v[64:67], v[80:81], off offset:1024
	global_load_dwordx4 v[68:71], v[82:83], off offset:1024
	global_load_dwordx4 v[72:75], v[80:81], off offset:2048
	global_load_dwordx4 v[76:79], v[82:83], off offset:2048
	s_waitcnt vmcnt(6)
	v_pk_fma_f32 v[50:51], v[50:51], s[40:41], v[54:55] op_sel_hi:[1,0,1]
	v_pk_fma_f32 v[48:49], v[48:49], s[40:41], v[52:53] op_sel_hi:[1,0,1]
	s_waitcnt vmcnt(4)
	v_pk_fma_f32 v[54:55], v[60:61], s[40:41], v[56:57] op_sel_hi:[1,0,1]
	v_pk_fma_f32 v[52:53], v[62:63], s[40:41], v[58:59] op_sel_hi:[1,0,1]
	v_add_f32_e32 v47, 0, v54
	v_add_f32_e32 v47, v47, v55
	v_add_f32_e32 v47, v47, v52
	s_waitcnt vmcnt(2)
	v_pk_fma_f32 v[58:59], v[64:65], s[40:41], v[68:69] op_sel_hi:[1,0,1]
	v_add_f32_e32 v47, v47, v53
	v_add_f32_e32 v47, v47, v58
	v_pk_fma_f32 v[56:57], v[66:67], s[40:41], v[70:71] op_sel_hi:[1,0,1]
	v_add_f32_e32 v47, v47, v59
	v_add_f32_e32 v47, v47, v56
	s_waitcnt vmcnt(0)
	v_pk_fma_f32 v[62:63], v[72:73], s[40:41], v[76:77] op_sel_hi:[1,0,1]
	v_add_f32_e32 v47, v47, v57
	v_add_f32_e32 v47, v47, v62
	v_pk_fma_f32 v[60:61], v[74:75], s[40:41], v[78:79] op_sel_hi:[1,0,1]
	v_add_f32_e32 v47, v47, v63
	v_add_f32_e32 v47, v47, v60
	v_add_f32_e32 v47, v47, v61
	v_add_f32_e32 v47, v47, v48
	v_add_f32_e32 v47, v47, v49
	v_add_f32_e32 v47, v47, v50
	v_add_f32_e32 v47, v47, v51
	s_nop 1
	v_add_f32_dpp v47, v47, v47 quad_perm:[1,0,3,2] row_mask:0xf bank_mask:0xf
	s_nop 1
	v_add_f32_dpp v47, v47, v47 quad_perm:[2,3,0,1] row_mask:0xf bank_mask:0xf
	s_nop 1
	v_add_f32_dpp v47, v47, v47 row_half_mirror row_mask:0xf bank_mask:0xf
	s_nop 1
	v_add_f32_dpp v47, v47, v47 row_mirror row_mask:0xf bank_mask:0xf
	v_mov_b32_e32 v64, v47
	s_nop 1
	v_permlane16_swap_b32_e32 v47, v64
	v_add_f32_e32 v47, v47, v64
	v_mov_b32_e32 v64, v47
	s_nop 1
	v_permlane32_swap_b32_e32 v47, v64
	v_add_f32_e32 v47, v47, v64
	v_mul_f32_e32 v64, 0x3a800000, v47
	v_pk_add_f32 v[54:55], v[54:55], v[64:65] op_sel_hi:[1,0] neg_lo:[0,1] neg_hi:[0,1]
	v_pk_add_f32 v[52:53], v[52:53], v[64:65] op_sel_hi:[1,0] neg_lo:[0,1] neg_hi:[0,1]
	v_pk_add_f32 v[58:59], v[58:59], v[64:65] op_sel_hi:[1,0] neg_lo:[0,1] neg_hi:[0,1]
	v_pk_add_f32 v[56:57], v[56:57], v[64:65] op_sel_hi:[1,0] neg_lo:[0,1] neg_hi:[0,1]
	v_pk_add_f32 v[62:63], v[62:63], v[64:65] op_sel_hi:[1,0] neg_lo:[0,1] neg_hi:[0,1]
	v_pk_add_f32 v[60:61], v[60:61], v[64:65] op_sel_hi:[1,0] neg_lo:[0,1] neg_hi:[0,1]
	v_pk_add_f32 v[50:51], v[50:51], v[64:65] op_sel_hi:[1,0] neg_lo:[0,1] neg_hi:[0,1]
	v_pk_add_f32 v[48:49], v[48:49], v[64:65] op_sel_hi:[1,0] neg_lo:[0,1] neg_hi:[0,1]
	v_pk_mul_f32 v[64:65], v[54:55], v[54:55]
	v_pk_mul_f32 v[66:67], v[52:53], v[52:53]
	v_add_f32_e32 v47, v64, v65
	v_add_f32_e32 v47, v66, v47
	v_pk_mul_f32 v[68:69], v[58:59], v[58:59]
	v_add_f32_e32 v47, v67, v47
	v_add_f32_e32 v47, v68, v47
	v_pk_mul_f32 v[70:71], v[56:57], v[56:57]
	v_add_f32_e32 v47, v69, v47
	v_add_f32_e32 v47, v70, v47
	v_pk_mul_f32 v[72:73], v[62:63], v[62:63]
	v_add_f32_e32 v47, v71, v47
	v_add_f32_e32 v47, v72, v47
	v_pk_mul_f32 v[74:75], v[60:61], v[60:61]
	v_add_f32_e32 v47, v73, v47
	v_add_f32_e32 v47, v74, v47
	v_pk_mul_f32 v[78:79], v[48:49], v[48:49]
	v_add_f32_e32 v47, v75, v47
	v_add_f32_e32 v47, v78, v47
	v_pk_mul_f32 v[76:77], v[50:51], v[50:51]
	v_add_f32_e32 v47, v79, v47
	v_add_f32_e32 v47, v76, v47
	v_add_f32_e32 v47, v77, v47
	s_nop 1
	v_add_f32_dpp v47, v47, v47 quad_perm:[1,0,3,2] row_mask:0xf bank_mask:0xf
	s_nop 1
	v_add_f32_dpp v47, v47, v47 quad_perm:[2,3,0,1] row_mask:0xf bank_mask:0xf
	s_nop 1
	v_add_f32_dpp v47, v47, v47 row_half_mirror row_mask:0xf bank_mask:0xf
	s_nop 1
	v_add_f32_dpp v47, v47, v47 row_mirror row_mask:0xf bank_mask:0xf
	v_mov_b32_e32 v64, v47
	s_nop 1
	v_permlane16_swap_b32_e32 v47, v64
	v_add_f32_e32 v47, v47, v64
	v_mov_b32_e32 v64, v47
	s_nop 1
	v_permlane32_swap_b32_e32 v47, v64
	v_add_f32_e32 v47, v47, v64
	v_lshlrev_b64 v[64:65], 11, v[32:33]
	v_add_u32_e32 v32, s33, v32
	v_cmp_lt_i32_e64 s[12:13], s5, v32
	v_lshl_add_u64 v[64:65], v[38:39], 0, v[64:65]
	s_waitcnt lgkmcnt(0)
	v_mov_b32_e32 v33, v47
	v_fmamk_f32 v33, v33, 0x3a800000, v46
	v_mul_f32_e32 v47, 0x4b800000, v33
	v_cmp_gt_f32_e32 vcc, s4, v33
	s_or_b64 s[14:15], s[12:13], s[14:15]
	s_nop 0
	v_cndmask_b32_e32 v33, v33, v47, vcc
	v_rsq_f32_e32 v33, v33
	s_nop 0
	v_mul_f32_e32 v47, 0x45800000, v33
	v_cndmask_b32_e32 v66, v33, v47, vcc
	v_pk_mul_f32 v[52:53], v[52:53], v[66:67] op_sel_hi:[1,0]
	v_pk_mul_f32 v[54:55], v[54:55], v[66:67] op_sel_hi:[1,0]
	v_pk_mul_f32 v[56:57], v[56:57], v[66:67] op_sel_hi:[1,0]
	v_pk_mul_f32 v[58:59], v[58:59], v[66:67] op_sel_hi:[1,0]
	v_pk_mul_f32 v[60:61], v[60:61], v[66:67] op_sel_hi:[1,0]
	v_pk_mul_f32 v[62:63], v[62:63], v[66:67] op_sel_hi:[1,0]
	v_pk_mul_f32 v[50:51], v[50:51], v[66:67] op_sel_hi:[1,0]
	v_pk_mul_f32 v[48:49], v[48:49], v[66:67] op_sel_hi:[1,0]
	v_pk_fma_f32 v[52:53], v[2:3], v[52:53], v[6:7]
	v_pk_fma_f32 v[54:55], v[0:1], v[54:55], v[4:5]
	v_pk_fma_f32 v[56:57], v[10:11], v[56:57], v[14:15]
	v_pk_fma_f32 v[58:59], v[8:9], v[58:59], v[12:13]
	v_pk_fma_f32 v[60:61], v[18:19], v[60:61], v[22:23]
	v_pk_fma_f32 v[62:63], v[16:17], v[62:63], v[20:21]
	v_pk_fma_f32 v[50:51], v[50:51], v[26:27], v[30:31]
	v_pk_fma_f32 v[48:49], v[48:49], v[24:25], v[28:29]
	v_cvt_pk_bf16_f32 v54, v54, v55
	v_cvt_pk_bf16_f32 v55, v52, v53
	v_cvt_pk_bf16_f32 v52, v58, v59
	v_cvt_pk_bf16_f32 v53, v56, v57
	v_cvt_pk_bf16_f32 v56, v62, v63
	v_cvt_pk_bf16_f32 v57, v60, v61
	v_cvt_pk_bf16_f32 v48, v48, v49
	v_cvt_pk_bf16_f32 v49, v50, v51
	global_store_dwordx2 v[64:65], v[54:55], off
	global_store_dwordx2 v[64:65], v[52:53], off offset:512
	global_store_dwordx2 v[64:65], v[56:57], off offset:1024
	global_store_dwordx2 v[64:65], v[48:49], off offset:1536
	s_andn2_b64 exec, exec, s[14:15]
	s_cbranch_execnz .LBB0_539

; DI float bflo(u32 u) { return __uint_as_float(u << 16); }
; DI float bfhi(u32 u) { return __uint_as_float(u & 0xffff0000u); }
; DI int opaque_tid() { int t = threadIdx.x; asm volatile("" : "+v"(t)); return t; }
; template <typename XT>
; DI void ln1_phase(const Params& p, const XT* __restrict__ xin, const float* __restrict__ mm, const float* __restrict__ gain, const float* __restrict__ bias,
;                   float* __restrict__ of, bf16* __restrict__ ob) {
;   const int tid = opaque_tid(), lane = tid & 63, w = tid >> 6;
;   for (int t = blockIdx.x * 4 + w; t < T_TOK; t += gridDim.x * 4) {
;     float v[16];
; #pragma unroll
;     for (int i = 0; i < 4; ++i) {
;       float4 a;
;       if constexpr (sizeof(XT) == 4) {
;         a = *(const float4*)((const float*)xin + (size_t)t * 1024 + 4 * lane + 256 * i);
;       } else {
;         const uint2 ab = *(const uint2*)((const bf16*)xin + (size_t)t * 1024 + 4 * lane + 256 * i);
;         a = make_float4(bflo(ab.x), bfhi(ab.x), bflo(ab.y), bfhi(ab.y));
;       }
;       float4 c = *(const float4*)(mm + (size_t)t * 1024 + 4 * lane + 256 * i);
;       v[4 * i] = DN_ALPHA * a.x + c.x; v[4 * i + 1] = DN_ALPHA * a.y + c.y; v[4 * i + 2] = DN_ALPHA * a.z + c.z; v[4 * i + 3] = DN_ALPHA * a.w + c.w;
;     }
;     float s = 0.f;
; #pragma unroll
;     for (int i = 0; i < 16; ++i) s += v[i];
;     float mu = wave_sum(s) * (1.f / 1024.f);
;     float q = 0.f;
; #pragma unroll
;     for (int i = 0; i < 16; ++i) { float d = v[i] - mu; q += d * d; }
;     float rstd = rsqrtf(wave_sum(q) * (1.f / 1024.f) + 1e-5f);
; #pragma unroll
;     for (int i = 0; i < 4; ++i) {
;       float4 gg = *(const float4*)(gain + 4 * lane + 256 * i);
;       float4 bb = *(const float4*)(bias + 4 * lane + 256 * i);
;       float4 o;
;       o.x = (v[4 * i] - mu) * rstd * gg.x + bb.x; o.y = (v[4 * i + 1] - mu) * rstd * gg.y + bb.y;
;       o.z = (v[4 * i + 2] - mu) * rstd * gg.z + bb.z; o.w = (v[4 * i + 3] - mu) * rstd * gg.w + bb.w;
;       if (of) *(float4*)(of + (size_t)t * 1024 + 4 * lane + 256 * i) = o;
;       if (ob) *(uint2*)(ob + (size_t)t * 1024 + 4 * lane + 256 * i) = make_uint2(pack2(o.x, o.y), pack2(o.z, o.w));
;     }
.LBB0_883:
	v_ashrrev_i32_e32 v33, 31, v32
	s_waitcnt vmcnt(9)
	v_lshlrev_b64 v[64:65], 11, v[32:33]
	v_lshl_add_u64 v[48:49], v[34:35], 0, v[64:65]
	global_load_dwordx2 v[66:67], v[48:49], off
	global_load_dwordx2 v[68:69], v[48:49], off offset:512
	global_load_dwordx2 v[70:71], v[48:49], off offset:1024
	global_load_dwordx2 v[72:73], v[48:49], off offset:1536
	v_lshlrev_b64 v[48:49], 12, v[32:33]
	v_lshl_add_u64 v[74:75], v[36:37], 0, v[48:49]
	global_load_dwordx4 v[48:51], v[74:75], off offset:3072
	global_load_dwordx4 v[52:55], v[74:75], off
	global_load_dwordx4 v[56:59], v[74:75], off offset:1024
	global_load_dwordx4 v[60:63], v[74:75], off offset:2048
	v_add_u32_e32 v32, s33, v32
	v_cmp_lt_i32_e64 s[8:9], s5, v32
	v_lshl_add_u64 v[64:65], v[38:39], 0, v[64:65]
	s_or_b64 s[12:13], s[8:9], s[12:13]
	s_waitcnt vmcnt(7)
	v_lshlrev_b32_e32 v74, 16, v66
	v_and_b32_e32 v75, 0xffff0000, v66
	v_lshlrev_b32_e32 v66, 16, v67
	v_and_b32_e32 v67, 0xffff0000, v67
	s_waitcnt vmcnt(2)
	v_pk_fma_f32 v[52:53], v[74:75], s[14:15], v[52:53] op_sel_hi:[1,0,1]
	v_pk_fma_f32 v[54:55], v[66:67], s[14:15], v[54:55] op_sel_hi:[1,0,1]
	v_add_f32_e32 v33, 0, v52
	v_add_f32_e32 v33, v53, v33
	v_lshlrev_b32_e32 v76, 16, v68
	v_and_b32_e32 v77, 0xffff0000, v68
	v_add_f32_e32 v33, v54, v33
	s_waitcnt vmcnt(1)
	v_pk_fma_f32 v[56:57], v[76:77], s[14:15], v[56:57] op_sel_hi:[1,0,1]
	v_add_f32_e32 v33, v55, v33
	v_lshlrev_b32_e32 v68, 16, v69
	v_and_b32_e32 v69, 0xffff0000, v69
	v_add_f32_e32 v33, v33, v56
	v_pk_fma_f32 v[58:59], v[68:69], s[14:15], v[58:59] op_sel_hi:[1,0,1]
	v_add_f32_e32 v33, v57, v33
	v_lshlrev_b32_e32 v78, 16, v70
	v_and_b32_e32 v79, 0xffff0000, v70
	v_add_f32_e32 v33, v58, v33
	s_waitcnt vmcnt(0)
	v_pk_fma_f32 v[60:61], v[78:79], s[14:15], v[60:61] op_sel_hi:[1,0,1]
	v_add_f32_e32 v33, v59, v33
	v_lshlrev_b32_e32 v70, 16, v71
	v_and_b32_e32 v71, 0xffff0000, v71
	v_add_f32_e32 v33, v33, v60
	v_pk_fma_f32 v[62:63], v[70:71], s[14:15], v[62:63] op_sel_hi:[1,0,1]
	v_add_f32_e32 v33, v61, v33
	v_lshlrev_b32_e32 v80, 16, v72
	v_and_b32_e32 v81, 0xffff0000, v72
	v_add_f32_e32 v33, v62, v33
	v_pk_fma_f32 v[48:49], v[80:81], s[14:15], v[48:49] op_sel_hi:[1,0,1]
	v_add_f32_e32 v33, v63, v33
	v_lshlrev_b32_e32 v72, 16, v73
	v_and_b32_e32 v73, 0xffff0000, v73
	v_add_f32_e32 v33, v33, v48
	v_pk_fma_f32 v[50:51], v[72:73], s[14:15], v[50:51] op_sel_hi:[1,0,1]
	v_add_f32_e32 v33, v49, v33
	v_add_f32_e32 v33, v50, v33
	v_add_f32_e32 v33, v51, v33
	s_nop 1
	v_add_f32_dpp v33, v33, v33 quad_perm:[1,0,3,2] row_mask:0xf bank_mask:0xf
	s_nop 1
	v_add_f32_dpp v33, v33, v33 quad_perm:[2,3,0,1] row_mask:0xf bank_mask:0xf
	s_nop 1
	v_add_f32_dpp v33, v33, v33 row_half_mirror row_mask:0xf bank_mask:0xf
	s_nop 1
	v_add_f32_dpp v33, v33, v33 row_mirror row_mask:0xf bank_mask:0xf
	v_mov_b32_e32 v47, v33
	s_nop 1
	v_permlane16_swap_b32_e32 v33, v47
	v_add_f32_e32 v33, v33, v47
	v_mov_b32_e32 v47, v33
	s_nop 1
	v_permlane32_swap_b32_e32 v33, v47
	v_add_f32_e32 v33, v33, v47
	v_mul_f32_e32 v66, 0x3a800000, v33
	v_pk_add_f32 v[52:53], v[52:53], v[66:67] op_sel_hi:[1,0] neg_lo:[0,1] neg_hi:[0,1]
	v_pk_add_f32 v[54:55], v[54:55], v[66:67] op_sel_hi:[1,0] neg_lo:[0,1] neg_hi:[0,1]
	v_pk_add_f32 v[56:57], v[56:57], v[66:67] op_sel_hi:[1,0] neg_lo:[0,1] neg_hi:[0,1]
	v_pk_add_f32 v[58:59], v[58:59], v[66:67] op_sel_hi:[1,0] neg_lo:[0,1] neg_hi:[0,1]
	v_pk_add_f32 v[60:61], v[60:61], v[66:67] op_sel_hi:[1,0] neg_lo:[0,1] neg_hi:[0,1]
	v_pk_add_f32 v[62:63], v[62:63], v[66:67] op_sel_hi:[1,0] neg_lo:[0,1] neg_hi:[0,1]
	v_pk_add_f32 v[50:51], v[50:51], v[66:67] op_sel_hi:[1,0] neg_lo:[0,1] neg_hi:[0,1]
	v_pk_add_f32 v[48:49], v[48:49], v[66:67] op_sel_hi:[1,0] neg_lo:[0,1] neg_hi:[0,1]
	v_pk_mul_f32 v[66:67], v[52:53], v[52:53]
	v_pk_mul_f32 v[68:69], v[54:55], v[54:55]
	v_add_f32_e32 v33, v66, v67
	v_add_f32_e32 v33, v68, v33
	v_pk_mul_f32 v[70:71], v[56:57], v[56:57]
	v_add_f32_e32 v33, v69, v33
	v_add_f32_e32 v33, v70, v33
	v_pk_mul_f32 v[72:73], v[58:59], v[58:59]
	v_add_f32_e32 v33, v71, v33
	v_add_f32_e32 v33, v72, v33
	v_pk_mul_f32 v[74:75], v[60:61], v[60:61]
	v_add_f32_e32 v33, v73, v33
	v_add_f32_e32 v33, v74, v33
	v_pk_mul_f32 v[76:77], v[62:63], v[62:63]
	v_add_f32_e32 v33, v75, v33
	v_add_f32_e32 v33, v76, v33
	v_pk_mul_f32 v[80:81], v[48:49], v[48:49]
	v_add_f32_e32 v33, v77, v33
	v_add_f32_e32 v33, v80, v33
	v_pk_mul_f32 v[78:79], v[50:51], v[50:51]
	v_add_f32_e32 v33, v81, v33
	v_add_f32_e32 v33, v78, v33
	v_add_f32_e32 v33, v79, v33
	s_nop 1
	v_add_f32_dpp v33, v33, v33 quad_perm:[1,0,3,2] row_mask:0xf bank_mask:0xf
	s_nop 1
	v_add_f32_dpp v33, v33, v33 quad_perm:[2,3,0,1] row_mask:0xf bank_mask:0xf
	s_nop 1
	v_add_f32_dpp v33, v33, v33 row_half_mirror row_mask:0xf bank_mask:0xf
	s_nop 1
	v_add_f32_dpp v33, v33, v33 row_mirror row_mask:0xf bank_mask:0xf
	v_mov_b32_e32 v47, v33
	s_nop 1
	v_permlane16_swap_b32_e32 v33, v47
	v_add_f32_e32 v33, v33, v47
	v_mov_b32_e32 v47, v33
	s_nop 1
	v_permlane32_swap_b32_e32 v33, v47
	v_add_f32_e32 v33, v33, v47
	v_fmamk_f32 v33, v33, 0x3a800000, v46
	v_mul_f32_e32 v47, 0x4b800000, v33
	v_cmp_gt_f32_e32 vcc, s4, v33
	s_nop 1
	v_cndmask_b32_e32 v33, v33, v47, vcc
	v_rsq_f32_e32 v33, v33
	s_nop 0
	v_mul_f32_e32 v47, 0x45800000, v33
	v_cndmask_b32_e32 v66, v33, v47, vcc
	v_pk_mul_f32 v[52:53], v[52:53], v[66:67] op_sel_hi:[1,0]
	v_pk_mul_f32 v[54:55], v[54:55], v[66:67] op_sel_hi:[1,0]
	v_pk_mul_f32 v[56:57], v[56:57], v[66:67] op_sel_hi:[1,0]
	v_pk_mul_f32 v[58:59], v[58:59], v[66:67] op_sel_hi:[1,0]
	v_pk_mul_f32 v[60:61], v[60:61], v[66:67] op_sel_hi:[1,0]
	v_pk_mul_f32 v[62:63], v[62:63], v[66:67] op_sel_hi:[1,0]
	v_pk_mul_f32 v[48:49], v[48:49], v[66:67] op_sel_hi:[1,0]
	v_pk_mul_f32 v[50:51], v[50:51], v[66:67] op_sel_hi:[1,0]
	v_pk_fma_f32 v[52:53], v[0:1], v[52:53], v[4:5]
	v_pk_fma_f32 v[54:55], v[2:3], v[54:55], v[6:7]
	v_pk_fma_f32 v[56:57], v[8:9], v[56:57], v[16:17]
	v_pk_fma_f32 v[58:59], v[10:11], v[58:59], v[18:19]
	v_pk_fma_f32 v[60:61], v[12:13], v[60:61], v[20:21]
	v_pk_fma_f32 v[62:63], v[14:15], v[62:63], v[22:23]
	v_pk_fma_f32 v[48:49], v[24:25], v[48:49], v[28:29]
	v_pk_fma_f32 v[50:51], v[26:27], v[50:51], v[30:31]
	v_cvt_pk_bf16_f32 v52, v52, v53
	v_cvt_pk_bf16_f32 v53, v54, v55
	v_cvt_pk_bf16_f32 v54, v56, v57
	v_cvt_pk_bf16_f32 v55, v58, v59
	v_cvt_pk_bf16_f32 v56, v60, v61
	v_cvt_pk_bf16_f32 v57, v62, v63
	v_cvt_pk_bf16_f32 v48, v48, v49
	v_cvt_pk_bf16_f32 v49, v50, v51
	global_store_dwordx2 v[64:65], v[52:53], off
	global_store_dwordx2 v[64:65], v[54:55], off offset:512
	global_store_dwordx2 v[64:65], v[56:57], off offset:1024
	global_store_dwordx2 v[64:65], v[48:49], off offset:1536
	s_andn2_b64 exec, exec, s[12:13]
	s_cbranch_execnz .LBB0_883

; DI float bflo(u32 u) { return __uint_as_float(u << 16); }
; DI float bfhi(u32 u) { return __uint_as_float(u & 0xffff0000u); }
; DI int opaque_tid() { int t = threadIdx.x; asm volatile("" : "+v"(t)); return t; }
; template <typename XT>
; DI void ln1_phase(const Params& p, const XT* __restrict__ xin, const float* __restrict__ mm, const float* __restrict__ gain, const float* __restrict__ bias,
;                   float* __restrict__ of, bf16* __restrict__ ob) {
;   const int tid = opaque_tid(), lane = tid & 63, w = tid >> 6;
;   for (int t = blockIdx.x * 4 + w; t < T_TOK; t += gridDim.x * 4) {
;     float v[16];
; #pragma unroll
;     for (int i = 0; i < 4; ++i) {
;       float4 a;
;       if constexpr (sizeof(XT) == 4) {
;         a = *(const float4*)((const float*)xin + (size_t)t * 1024 + 4 * lane + 256 * i);
;       } else {
;         const uint2 ab = *(const uint2*)((const bf16*)xin + (size_t)t * 1024 + 4 * lane + 256 * i);
;         a = make_float4(bflo(ab.x), bfhi(ab.x), bflo(ab.y), bfhi(ab.y));
;       }
;       float4 c = *(const float4*)(mm + (size_t)t * 1024 + 4 * lane + 256 * i);
;       v[4 * i] = DN_ALPHA * a.x + c.x; v[4 * i + 1] = DN_ALPHA * a.y + c.y; v[4 * i + 2] = DN_ALPHA * a.z + c.z; v[4 * i + 3] = DN_ALPHA * a.w + c.w;
;     }
;     float s = 0.f;
; #pragma unroll
;     for (int i = 0; i < 16; ++i) s += v[i];
;     float mu = wave_sum(s) * (1.f / 1024.f);
;     float q = 0.f;
; #pragma unroll
;     for (int i = 0; i < 16; ++i) { float d = v[i] - mu; q += d * d; }
;     float rstd = rsqrtf(wave_sum(q) * (1.f / 1024.f) + 1e-5f);
; #pragma unroll
;     for (int i = 0; i < 4; ++i) {
;       float4 gg = *(const float4*)(gain + 4 * lane + 256 * i);
;       float4 bb = *(const float4*)(bias + 4 * lane + 256 * i);
;       float4 o;
;       o.x = (v[4 * i] - mu) * rstd * gg.x + bb.x; o.y = (v[4 * i + 1] - mu) * rstd * gg.y + bb.y;
;       o.z = (v[4 * i + 2] - mu) * rstd * gg.z + bb.z; o.w = (v[4 * i + 3] - mu) * rstd * gg.w + bb.w;
;       if (of) *(float4*)(of + (size_t)t * 1024 + 4 * lane + 256 * i) = o;
;       if (ob) *(uint2*)(ob + (size_t)t * 1024 + 4 * lane + 256 * i) = make_uint2(pack2(o.x, o.y), pack2(o.z, o.w));
;     }
.LBB0_1707:
	v_ashrrev_i32_e32 v33, 31, v32
	v_lshlrev_b64 v[40:41], 11, v[32:33]
	v_lshl_add_u64 v[40:41], v[34:35], 0, v[40:41]
	global_load_dwordx2 v[66:67], v[40:41], off
	global_load_dwordx2 v[68:69], v[40:41], off offset:512
	global_load_dwordx2 v[70:71], v[40:41], off offset:1024
	global_load_dwordx2 v[72:73], v[40:41], off offset:1536
	v_lshlrev_b64 v[40:41], 12, v[32:33]
	v_lshl_add_u64 v[74:75], v[36:37], 0, v[40:41]
	global_load_dwordx4 v[42:45], v[74:75], off
	global_load_dwordx4 v[46:49], v[74:75], off offset:1024
	global_load_dwordx4 v[50:53], v[74:75], off offset:2048
	global_load_dwordx4 v[54:57], v[74:75], off offset:3072
	s_and_b64 vcc, exec, s[0:1]
	s_waitcnt vmcnt(7)
	v_lshlrev_b32_e32 v74, 16, v66
	v_and_b32_e32 v75, 0xffff0000, v66
	v_lshlrev_b32_e32 v66, 16, v67
	s_waitcnt vmcnt(3)
	v_pk_fma_f32 v[42:43], v[74:75], s[4:5], v[42:43] op_sel_hi:[1,0,1]
	v_and_b32_e32 v67, 0xffff0000, v67
	v_add_f32_e32 v33, 0, v42
	v_pk_fma_f32 v[44:45], v[66:67], s[4:5], v[44:45] op_sel_hi:[1,0,1]
	v_add_f32_e32 v33, v43, v33
	v_lshlrev_b32_e32 v76, 16, v68
	v_and_b32_e32 v77, 0xffff0000, v68
	v_add_f32_e32 v33, v44, v33
	s_waitcnt vmcnt(2)
	v_pk_fma_f32 v[46:47], v[76:77], s[4:5], v[46:47] op_sel_hi:[1,0,1]
	v_add_f32_e32 v33, v45, v33
	v_lshlrev_b32_e32 v68, 16, v69
	v_and_b32_e32 v69, 0xffff0000, v69
	v_add_f32_e32 v33, v33, v46
	v_pk_fma_f32 v[48:49], v[68:69], s[4:5], v[48:49] op_sel_hi:[1,0,1]
	v_add_f32_e32 v33, v47, v33
	v_lshlrev_b32_e32 v78, 16, v70
	v_and_b32_e32 v79, 0xffff0000, v70
	v_add_f32_e32 v33, v48, v33
	s_waitcnt vmcnt(1)
	v_pk_fma_f32 v[66:67], v[78:79], s[4:5], v[50:51] op_sel_hi:[1,0,1]
	v_add_f32_e32 v33, v49, v33
	v_lshlrev_b32_e32 v70, 16, v71
	v_and_b32_e32 v71, 0xffff0000, v71
	v_add_f32_e32 v33, v33, v66
	v_pk_fma_f32 v[68:69], v[70:71], s[4:5], v[52:53] op_sel_hi:[1,0,1]
	v_add_f32_e32 v33, v67, v33
	v_lshlrev_b32_e32 v80, 16, v72
	v_and_b32_e32 v81, 0xffff0000, v72
	v_add_f32_e32 v33, v68, v33
	s_waitcnt vmcnt(0)
	v_pk_fma_f32 v[70:71], v[80:81], s[4:5], v[54:55] op_sel_hi:[1,0,1]
	v_add_f32_e32 v33, v69, v33
	v_lshlrev_b32_e32 v72, 16, v73
	v_and_b32_e32 v73, 0xffff0000, v73
	v_add_f32_e32 v33, v33, v70
	v_pk_fma_f32 v[72:73], v[72:73], s[4:5], v[56:57] op_sel_hi:[1,0,1]
	v_add_f32_e32 v33, v71, v33
	v_add_f32_e32 v33, v72, v33
	v_add_f32_e32 v33, v73, v33
	s_nop 1
	v_add_f32_dpp v33, v33, v33 quad_perm:[1,0,3,2] row_mask:0xf bank_mask:0xf
	s_nop 1
	v_add_f32_dpp v33, v33, v33 quad_perm:[2,3,0,1] row_mask:0xf bank_mask:0xf
	s_nop 1
	v_add_f32_dpp v33, v33, v33 row_half_mirror row_mask:0xf bank_mask:0xf
	s_nop 1
	v_add_f32_dpp v33, v33, v33 row_mirror row_mask:0xf bank_mask:0xf
	v_mov_b32_e32 v50, v33
	s_nop 1
	v_permlane16_swap_b32_e32 v33, v50
	v_add_f32_e32 v33, v33, v50
	v_mov_b32_e32 v50, v33
	s_nop 1
	v_permlane32_swap_b32_e32 v33, v50
	v_add_f32_e32 v33, v33, v50
	v_mul_f32_e32 v74, 0x3a800000, v33
	v_pk_add_f32 v[54:55], v[42:43], v[74:75] op_sel_hi:[1,0] neg_lo:[0,1] neg_hi:[0,1]
	v_pk_add_f32 v[56:57], v[44:45], v[74:75] op_sel_hi:[1,0] neg_lo:[0,1] neg_hi:[0,1]
	v_pk_add_f32 v[50:51], v[46:47], v[74:75] op_sel_hi:[1,0] neg_lo:[0,1] neg_hi:[0,1]
	v_pk_add_f32 v[46:47], v[66:67], v[74:75] op_sel_hi:[1,0] neg_lo:[0,1] neg_hi:[0,1]
	v_pk_mul_f32 v[66:67], v[54:55], v[54:55]
	v_pk_add_f32 v[52:53], v[48:49], v[74:75] op_sel_hi:[1,0] neg_lo:[0,1] neg_hi:[0,1]
	v_pk_add_f32 v[48:49], v[68:69], v[74:75] op_sel_hi:[1,0] neg_lo:[0,1] neg_hi:[0,1]
	v_pk_mul_f32 v[68:69], v[56:57], v[56:57]
	v_add_f32_e32 v33, v66, v67
	v_add_f32_e32 v33, v68, v33
	v_pk_add_f32 v[42:43], v[70:71], v[74:75] op_sel_hi:[1,0] neg_lo:[0,1] neg_hi:[0,1]
	v_pk_mul_f32 v[70:71], v[50:51], v[50:51]
	v_add_f32_e32 v33, v69, v33
	v_add_f32_e32 v33, v70, v33
	v_pk_add_f32 v[44:45], v[72:73], v[74:75] op_sel_hi:[1,0] neg_lo:[0,1] neg_hi:[0,1]
	v_pk_mul_f32 v[72:73], v[52:53], v[52:53]
	v_add_f32_e32 v33, v71, v33
	v_add_f32_e32 v33, v72, v33
	v_pk_mul_f32 v[74:75], v[46:47], v[46:47]
	v_add_f32_e32 v33, v73, v33
	v_add_f32_e32 v33, v74, v33
	v_pk_mul_f32 v[76:77], v[48:49], v[48:49]
	v_add_f32_e32 v33, v75, v33
	v_add_f32_e32 v33, v76, v33
	v_pk_mul_f32 v[78:79], v[42:43], v[42:43]
	v_add_f32_e32 v33, v77, v33
	v_add_f32_e32 v33, v78, v33
	v_pk_mul_f32 v[80:81], v[44:45], v[44:45]
	v_add_f32_e32 v33, v79, v33
	v_add_f32_e32 v33, v80, v33
	v_add_f32_e32 v33, v81, v33
	s_nop 1
	v_add_f32_dpp v33, v33, v33 quad_perm:[1,0,3,2] row_mask:0xf bank_mask:0xf
	s_nop 1
	v_add_f32_dpp v33, v33, v33 quad_perm:[2,3,0,1] row_mask:0xf bank_mask:0xf
	s_nop 1
	v_add_f32_dpp v33, v33, v33 row_half_mirror row_mask:0xf bank_mask:0xf
	s_nop 1
	v_add_f32_dpp v33, v33, v33 row_mirror row_mask:0xf bank_mask:0xf
	v_mov_b32_e32 v65, v33
	s_nop 1
	v_permlane16_swap_b32_e32 v33, v65
	v_add_f32_e32 v33, v33, v65
	v_mov_b32_e32 v65, v33
	s_nop 1
	v_permlane32_swap_b32_e32 v33, v65
	v_add_f32_e32 v33, v33, v65
	s_cbranch_vccnz .LBB0_1706
	s_waitcnt lgkmcnt(0)
	v_fmamk_f32 v33, v33, 0x3a800000, v64
	v_mul_f32_e32 v65, 0x4b800000, v33
	v_cmp_gt_f32_e32 vcc, s5, v33
	v_lshl_add_u64 v[66:67], v[38:39], 0, v[40:41]
	s_nop 0
	v_cndmask_b32_e32 v33, v33, v65, vcc
	v_rsq_f32_e32 v33, v33
	s_nop 0
	v_mul_f32_e32 v40, 0x45800000, v33
	v_cndmask_b32_e32 v68, v33, v40, vcc
	v_pk_mul_f32 v[40:41], v[54:55], v[68:69] op_sel_hi:[1,0]
	v_pk_mul_f32 v[56:57], v[56:57], v[68:69] op_sel_hi:[1,0]
	v_pk_fma_f32 v[54:55], v[0:1], v[40:41], v[4:5]
	v_pk_mul_f32 v[40:41], v[50:51], v[68:69] op_sel_hi:[1,0]
	v_pk_fma_f32 v[56:57], v[2:3], v[56:57], v[6:7]
	v_pk_fma_f32 v[50:51], v[8:9], v[40:41], v[16:17]
	v_pk_mul_f32 v[40:41], v[52:53], v[68:69] op_sel_hi:[1,0]
	global_store_dwordx4 v[66:67], v[54:57], off
	v_pk_fma_f32 v[52:53], v[10:11], v[40:41], v[18:19]
	v_pk_mul_f32 v[40:41], v[46:47], v[68:69] op_sel_hi:[1,0]
	global_store_dwordx4 v[66:67], v[50:53], off offset:1024
	v_pk_fma_f32 v[46:47], v[12:13], v[40:41], v[20:21]
	v_pk_mul_f32 v[40:41], v[48:49], v[68:69] op_sel_hi:[1,0]
	s_nop 0
	v_pk_fma_f32 v[48:49], v[14:15], v[40:41], v[22:23]
	v_pk_mul_f32 v[40:41], v[42:43], v[68:69] op_sel_hi:[1,0]
	v_pk_mul_f32 v[42:43], v[44:45], v[68:69] op_sel_hi:[1,0]
	v_pk_fma_f32 v[40:41], v[24:25], v[40:41], v[28:29]
	v_pk_fma_f32 v[42:43], v[26:27], v[42:43], v[30:31]
	global_store_dwordx4 v[66:67], v[46:49], off offset:2048
	global_store_dwordx4 v[66:67], v[40:43], off offset:3072
	s_branch .LBB0_1706
